# v33 + compute-wave priority raised before the load-segment barrier and the redundant post-barrier lgkmcnt wait dropped (first MFMA issues right at release)
# speedup vs baseline: 1.0221x; 1.0068x over previous
; #define PG8_STAGE(bufoff, gbase, voff) do { _Pragma("unroll") for (int _i = 0; _i < 2; ++_i) \
;         __builtin_amdgcn_global_load_lds((const unsigned*)((const char*)(gbase) + (voff)[_i]), (LAS unsigned*)(lds + (bufoff) + ldsw + _i * 8192), 16, 0, 0); } while (0)
; #define PG8_LDA(dst, b, h) do { _Pragma("unroll") for (int m = 0; m < 4; ++m) _Pragma("unroll") for (int k = 0; k < 2; ++k) dst[m][k] = *(const LAS bf16x8*)(lds + PG8_SA(b, h) + aoff + m * 2048 + k * 1024); } while (0)
; #define PG8_LDB(dst, b, h) do { _Pragma("unroll") for (int n = 0; n < 2; ++n) _Pragma("unroll") for (int k = 0; k < 2; ++k) dst[n][k] = *(const LAS bf16x8*)(lds + PG8_SB(b, h) + boff + n * 2048 + k * 1024); } while (0)
; #define PG8_MMA(ai, bj, At, Bt) do { __builtin_amdgcn_s_setprio(1); _Pragma("unroll") for (int m = 0; m < 4; ++m) _Pragma("unroll") for (int n = 0; n < 2; ++n) _Pragma("unroll") for (int k = 0; k < 2; ++k) \
;         acc[ai][bj][m][n] = __builtin_amdgcn_mfma_f32_16x16x32_bf16(Bt[n][k], At[m][k], acc[ai][bj][m][n], 0, 0, 0); __builtin_amdgcn_s_setprio(0); } while (0)
; #define PG8_WAIT_V(n) asm volatile("s_waitcnt vmcnt(" #n ")" ::: "memory")
; template <class Epi, class Sched>
; __device__ __forceinline__ void gemm_phase(LAS unsigned char* lds, const Gemm g, Sched S, const Epi& E) {
;     ...
;             const bool last = (t == nt - 2);
;             const char* a1 = cA + (size_t)(t + 1) * kstep;
;             const char* a2 = last ? nA : cA + (size_t)(t + 2) * kstep; const char* b2 = last ? nB : cB + (size_t)(t + 2) * kstep;
;             const char* a3 = a2 + kstep; const char* b3 = b2 + kstep;
;             PG8_LDB(B0, 0, 0); PG8_LDB(B1, 0, 1); PG8_SCHED; PG8_LDA(At, 0, 0); PG8_STAGE(PG8_SA(1, 1), a1 + hstepA, voffA);
;             PG8_WAIT_V(8); PG8_WAIT_L(0); PG8_BAR; PG8_MMA(0, 0, At, B0); PG8_MMA(0, 1, At, B1); PG8_BAR; PG8_SCHED;
;             PG8_LDA(At, 0, 1); PG8_STAGE(PG8_SB(0, 0), b2, voffB); PG8_STAGE(PG8_SB(0, 1), b2 + hstepB, voffB); PG8_STAGE(PG8_SA(0, 0), a2, voffA);
;             PG8_WAIT_V(8); PG8_WAIT_L(0); PG8_BAR; PG8_MMA(1, 0, At, B0); PG8_MMA(1, 1, At, B1); PG8_BAR; PG8_SCHED;
;             PG8_LDB(B0, 1, 0); PG8_LDB(B1, 1, 1); PG8_SCHED; PG8_LDA(At, 1, 0); PG8_STAGE(PG8_SA(0, 1), a2 + hstepA, voffA);
;             PG8_WAIT_V(8); PG8_WAIT_L(0); PG8_BAR; PG8_MMA(0, 0, At, B0); PG8_MMA(0, 1, At, B1); PG8_BAR; PG8_SCHED;
.LBB0_630:
	s_add_i32 s67, s65, 2
	s_add_u32 s2, s0, 0xfffc0080
	s_addc_u32 s3, s1, -1
	s_add_i32 s99, 0, 0x10000
	s_cmp_eq_u32 s70, s65
	s_cselect_b32 vcc_hi, s55, s3
	s_cselect_b32 vcc_lo, s54, s2
	s_cselect_b32 s77, s45, s64
	s_cselect_b32 s76, s44, s63
	s_add_i32 s65, 0, 0x14000
	v_add_u32_e32 v142, s99, v180
	v_add_u32_e32 v158, s65, v180
	ds_read_b128 v[130:133], v142
	ds_read_b128 v[134:137], v142 offset:1024
	ds_read_b128 v[138:141], v142 offset:2048
	ds_read_b128 v[142:145], v142 offset:3072
	ds_read_b128 v[146:149], v158
	ds_read_b128 v[150:153], v158 offset:1024
	ds_read_b128 v[154:157], v158 offset:2048
	ds_read_b128 v[158:161], v158 offset:3072
	s_add_i32 m0, s53, 0xc000
	ds_read_b128 v[174:177], v191
	ds_read_b128 v[192:195], v191 offset:1024
	ds_read_b128 v[196:199], v191 offset:2048
	ds_read_b128 v[200:203], v191 offset:3072
	ds_read_b128 v[204:207], v191 offset:4096
	ds_read_b128 v[208:211], v191 offset:5120
	ds_read_b128 v[212:215], v191 offset:6144
	ds_read_b128 v[216:219], v191 offset:7168
	global_load_lds_dwordx4 v172, s[0:1]
	s_add_i32 m0, s53, 0xe000
	s_nop 0
	global_load_lds_dwordx4 v170, s[0:1]
	s_waitcnt vmcnt(8)
	s_waitcnt lgkmcnt(0)
	s_setprio 1
	s_barrier
	v_mfma_f32_16x16x32_bf16 v[126:129], v[130:133], v[174:177], v[126:129]
	v_mfma_f32_16x16x32_bf16 v[122:125], v[138:141], v[174:177], v[122:125]
	v_mfma_f32_16x16x32_bf16 v[114:117], v[130:133], v[196:199], v[114:117]
	v_mfma_f32_16x16x32_bf16 v[106:109], v[138:141], v[196:199], v[106:109]
	v_mfma_f32_16x16x32_bf16 v[98:101], v[130:133], v[204:207], v[98:101]
	v_mfma_f32_16x16x32_bf16 v[90:93], v[138:141], v[204:207], v[90:93]
	v_mfma_f32_16x16x32_bf16 v[82:85], v[130:133], v[212:215], v[82:85]
	v_mfma_f32_16x16x32_bf16 v[74:77], v[138:141], v[212:215], v[74:77]
	v_mfma_f32_16x16x32_bf16 v[126:129], v[134:137], v[192:195], v[126:129]
	v_mfma_f32_16x16x32_bf16 v[122:125], v[142:145], v[192:195], v[122:125]
	v_mfma_f32_16x16x32_bf16 v[114:117], v[134:137], v[200:203], v[114:117]
	v_mfma_f32_16x16x32_bf16 v[106:109], v[142:145], v[200:203], v[106:109]
	v_mfma_f32_16x16x32_bf16 v[98:101], v[134:137], v[208:211], v[98:101]
	v_mfma_f32_16x16x32_bf16 v[90:93], v[142:145], v[208:211], v[90:93]
	v_mfma_f32_16x16x32_bf16 v[82:85], v[134:137], v[216:219], v[82:85]
	v_mfma_f32_16x16x32_bf16 v[74:77], v[142:145], v[216:219], v[74:77]
	s_setprio 0
	s_setprio 1
	v_mfma_f32_16x16x32_bf16 v[118:121], v[146:149], v[174:177], v[118:121]
	v_mfma_f32_16x16x32_bf16 v[110:113], v[154:157], v[174:177], v[110:113]
	v_mfma_f32_16x16x32_bf16 v[102:105], v[146:149], v[196:199], v[102:105]
	v_mfma_f32_16x16x32_bf16 v[94:97], v[154:157], v[196:199], v[94:97]
	v_mfma_f32_16x16x32_bf16 v[86:89], v[146:149], v[204:207], v[86:89]
	v_mfma_f32_16x16x32_bf16 v[78:81], v[154:157], v[204:207], v[78:81]
	v_mfma_f32_16x16x32_bf16 v[70:73], v[146:149], v[212:215], v[70:73]
	v_mfma_f32_16x16x32_bf16 v[66:69], v[154:157], v[212:215], v[66:69]
	v_mfma_f32_16x16x32_bf16 v[118:121], v[150:153], v[192:195], v[118:121]
	v_mfma_f32_16x16x32_bf16 v[110:113], v[158:161], v[192:195], v[110:113]
	v_mfma_f32_16x16x32_bf16 v[102:105], v[150:153], v[200:203], v[102:105]
	v_mfma_f32_16x16x32_bf16 v[94:97], v[158:161], v[200:203], v[94:97]
	s_setprio 2
	s_barrier
	v_mfma_f32_16x16x32_bf16 v[86:89], v[150:153], v[208:211], v[86:89]
	v_mfma_f32_16x16x32_bf16 v[78:81], v[158:161], v[208:211], v[78:81]
	v_mfma_f32_16x16x32_bf16 v[70:73], v[150:153], v[216:219], v[70:73]
	v_mfma_f32_16x16x32_bf16 v[66:69], v[158:161], v[216:219], v[66:69]
	s_setprio 0
	s_add_i32 s2, s99, s43
	s_mov_b32 m0, s2
	ds_read_b128 v[174:177], v191 offset:16384
	ds_read_b128 v[192:195], v191 offset:17408
	ds_read_b128 v[196:199], v191 offset:18432
	ds_read_b128 v[200:203], v191 offset:19456
	ds_read_b128 v[204:207], v191 offset:20480
	ds_read_b128 v[208:211], v191 offset:21504
	ds_read_b128 v[212:215], v191 offset:22528
	ds_read_b128 v[216:219], v191 offset:23552
	global_load_lds_dwordx4 v0, s[76:77]
	s_add_i32 m0, s2, 0x2000
	s_add_u32 s2, s76, 0x40000
	s_addc_u32 s3, s77, 0
	s_add_i32 s65, s65, s43
	global_load_lds_dwordx4 v168, s[76:77]
	s_mov_b32 m0, s65
	s_nop 0
	global_load_lds_dwordx4 v0, s[2:3]
	s_add_i32 m0, s65, 0x2000
	s_nop 0
	global_load_lds_dwordx4 v168, s[2:3]
	s_mov_b32 m0, s53
	s_nop 0
	global_load_lds_dwordx4 v164, vcc
	s_mov_b32 m0, s85
	s_nop 0
	global_load_lds_dwordx4 v166, vcc
	s_waitcnt vmcnt(8)
	s_waitcnt lgkmcnt(0)
	s_setprio 1
	s_barrier
	v_mfma_f32_16x16x32_bf16 v[62:65], v[130:133], v[174:177], v[62:65]
	v_mfma_f32_16x16x32_bf16 v[58:61], v[138:141], v[174:177], v[58:61]
	v_mfma_f32_16x16x32_bf16 v[50:53], v[130:133], v[196:199], v[50:53]
	v_mfma_f32_16x16x32_bf16 v[42:45], v[138:141], v[196:199], v[42:45]
	v_mfma_f32_16x16x32_bf16 v[34:37], v[130:133], v[204:207], v[34:37]
	v_mfma_f32_16x16x32_bf16 v[26:29], v[138:141], v[204:207], v[26:29]
	v_mfma_f32_16x16x32_bf16 v[18:21], v[130:133], v[212:215], v[18:21]
	v_mfma_f32_16x16x32_bf16 v[10:13], v[138:141], v[212:215], v[10:13]
	v_mfma_f32_16x16x32_bf16 v[62:65], v[134:137], v[192:195], v[62:65]
	v_mfma_f32_16x16x32_bf16 v[58:61], v[142:145], v[192:195], v[58:61]
	v_mfma_f32_16x16x32_bf16 v[50:53], v[134:137], v[200:203], v[50:53]
	v_mfma_f32_16x16x32_bf16 v[42:45], v[142:145], v[200:203], v[42:45]
	v_mfma_f32_16x16x32_bf16 v[34:37], v[134:137], v[208:211], v[34:37]
	v_mfma_f32_16x16x32_bf16 v[26:29], v[142:145], v[208:211], v[26:29]
	v_mfma_f32_16x16x32_bf16 v[18:21], v[134:137], v[216:219], v[18:21]
	v_mfma_f32_16x16x32_bf16 v[10:13], v[142:145], v[216:219], v[10:13]
	s_setprio 0
	s_setprio 1
	v_mfma_f32_16x16x32_bf16 v[54:57], v[146:149], v[174:177], v[54:57]
	v_mfma_f32_16x16x32_bf16 v[46:49], v[154:157], v[174:177], v[46:49]
	v_mfma_f32_16x16x32_bf16 v[38:41], v[146:149], v[196:199], v[38:41]
	v_mfma_f32_16x16x32_bf16 v[30:33], v[154:157], v[196:199], v[30:33]
	v_mfma_f32_16x16x32_bf16 v[22:25], v[146:149], v[204:207], v[22:25]
	v_mfma_f32_16x16x32_bf16 v[14:17], v[154:157], v[204:207], v[14:17]
	v_mfma_f32_16x16x32_bf16 v[6:9], v[146:149], v[212:215], v[6:9]
	v_mfma_f32_16x16x32_bf16 v[2:5], v[154:157], v[212:215], v[2:5]
	v_mfma_f32_16x16x32_bf16 v[54:57], v[150:153], v[192:195], v[54:57]
	v_mfma_f32_16x16x32_bf16 v[46:49], v[158:161], v[192:195], v[46:49]
	v_mfma_f32_16x16x32_bf16 v[38:41], v[150:153], v[200:203], v[38:41]
	v_mfma_f32_16x16x32_bf16 v[30:33], v[158:161], v[200:203], v[30:33]
	s_setprio 2
	s_barrier
; #define PG8_STAGE(bufoff, gbase, voff) do { _Pragma("unroll") for (int _i = 0; _i < 2; ++_i) \
;         __builtin_amdgcn_global_load_lds((const unsigned*)((const char*)(gbase) + (voff)[_i]), (LAS unsigned*)(lds + (bufoff) + ldsw + _i * 8192), 16, 0, 0); } while (0)
; #define PG8_LDA(dst, b, h) do { _Pragma("unroll") for (int m = 0; m < 4; ++m) _Pragma("unroll") for (int k = 0; k < 2; ++k) dst[m][k] = *(const LAS bf16x8*)(lds + PG8_SA(b, h) + aoff + m * 2048 + k * 1024); } while (0)
; #define PG8_LDB(dst, b, h) do { _Pragma("unroll") for (int n = 0; n < 2; ++n) _Pragma("unroll") for (int k = 0; k < 2; ++k) dst[n][k] = *(const LAS bf16x8*)(lds + PG8_SB(b, h) + boff + n * 2048 + k * 1024); } while (0)
; #define PG8_MMA(ai, bj, At, Bt) do { __builtin_amdgcn_s_setprio(1); _Pragma("unroll") for (int m = 0; m < 4; ++m) _Pragma("unroll") for (int n = 0; n < 2; ++n) _Pragma("unroll") for (int k = 0; k < 2; ++k) \
;         acc[ai][bj][m][n] = __builtin_amdgcn_mfma_f32_16x16x32_bf16(Bt[n][k], At[m][k], acc[ai][bj][m][n], 0, 0, 0); __builtin_amdgcn_s_setprio(0); } while (0)
; #define PG8_WAIT_V(n) asm volatile("s_waitcnt vmcnt(" #n ")" ::: "memory")
; #define PG8_WAIT_L(n) asm volatile("s_waitcnt lgkmcnt(" #n ")" ::: "memory")
; #define PG8_BAR __builtin_amdgcn_s_barrier()
; #define PG8_SCHED __builtin_amdgcn_sched_barrier(0)
; template <class Epi, class Sched>
; __device__ __forceinline__ void gemm_phase(LAS unsigned char* lds, const Gemm g, Sched S, const Epi& E) {
;     ...
;             PG8_WAIT_V(8); PG8_WAIT_L(0); PG8_BAR; PG8_MMA(1, 0, At, B0); PG8_MMA(1, 1, At, B1); PG8_BAR; PG8_SCHED;
;             PG8_LDB(B0, 1, 0); PG8_LDB(B1, 1, 1); PG8_SCHED; PG8_LDA(At, 1, 0); PG8_STAGE(PG8_SA(0, 1), a2 + hstepA, voffA);
;             PG8_WAIT_V(8); PG8_WAIT_L(0); PG8_BAR; PG8_MMA(0, 0, At, B0); PG8_MMA(0, 1, At, B1); PG8_BAR; PG8_SCHED;
	v_mfma_f32_16x16x32_bf16 v[22:25], v[150:153], v[208:211], v[22:25]
	v_mfma_f32_16x16x32_bf16 v[14:17], v[158:161], v[208:211], v[14:17]
	v_mfma_f32_16x16x32_bf16 v[6:9], v[150:153], v[216:219], v[6:9]
	v_mfma_f32_16x16x32_bf16 v[2:5], v[158:161], v[216:219], v[2:5]
	s_setprio 0
	s_add_i32 s65, 0, 0x18000
	s_add_i32 s99, 0, 0x1c000
	v_add_u32_e32 v142, s65, v180
	v_add_u32_e32 v158, s99, v180
	ds_read_b128 v[130:133], v142
	ds_read_b128 v[134:137], v142 offset:1024
	ds_read_b128 v[138:141], v142 offset:2048
	ds_read_b128 v[142:145], v142 offset:3072
	ds_read_b128 v[146:149], v158
	ds_read_b128 v[150:153], v158 offset:1024
	ds_read_b128 v[154:157], v158 offset:2048
	ds_read_b128 v[158:161], v158 offset:3072
	s_add_u32 s2, vcc_lo, 0x40000
	s_addc_u32 s3, vcc_hi, 0
	s_mov_b32 m0, s18
	ds_read_b128 v[174:177], v191 offset:32768
	ds_read_b128 v[192:195], v191 offset:33792
	ds_read_b128 v[196:199], v191 offset:34816
	ds_read_b128 v[200:203], v191 offset:35840
	ds_read_b128 v[204:207], v191 offset:36864
	ds_read_b128 v[208:211], v191 offset:37888
	ds_read_b128 v[212:215], v191 offset:38912
	ds_read_b128 v[216:219], v191 offset:39936
	global_load_lds_dwordx4 v164, s[2:3]
	s_mov_b32 m0, s19
	s_nop 0
	global_load_lds_dwordx4 v166, s[2:3]
	s_waitcnt vmcnt(8)
	s_waitcnt lgkmcnt(0)
	s_setprio 1
	s_barrier
	v_mfma_f32_16x16x32_bf16 v[126:129], v[130:133], v[174:177], v[126:129]
	v_mfma_f32_16x16x32_bf16 v[122:125], v[138:141], v[174:177], v[122:125]
	v_mfma_f32_16x16x32_bf16 v[114:117], v[130:133], v[196:199], v[114:117]
	v_mfma_f32_16x16x32_bf16 v[106:109], v[138:141], v[196:199], v[106:109]
	v_mfma_f32_16x16x32_bf16 v[98:101], v[130:133], v[204:207], v[98:101]
	v_mfma_f32_16x16x32_bf16 v[90:93], v[138:141], v[204:207], v[90:93]
	v_mfma_f32_16x16x32_bf16 v[82:85], v[130:133], v[212:215], v[82:85]
	v_mfma_f32_16x16x32_bf16 v[74:77], v[138:141], v[212:215], v[74:77]
	v_mfma_f32_16x16x32_bf16 v[126:129], v[134:137], v[192:195], v[126:129]
	v_mfma_f32_16x16x32_bf16 v[122:125], v[142:145], v[192:195], v[122:125]
	v_mfma_f32_16x16x32_bf16 v[114:117], v[134:137], v[200:203], v[114:117]
	v_mfma_f32_16x16x32_bf16 v[106:109], v[142:145], v[200:203], v[106:109]
	v_mfma_f32_16x16x32_bf16 v[98:101], v[134:137], v[208:211], v[98:101]
	v_mfma_f32_16x16x32_bf16 v[90:93], v[142:145], v[208:211], v[90:93]
	v_mfma_f32_16x16x32_bf16 v[82:85], v[134:137], v[216:219], v[82:85]
	v_mfma_f32_16x16x32_bf16 v[74:77], v[142:145], v[216:219], v[74:77]
	s_setprio 0
	s_setprio 1
	v_mfma_f32_16x16x32_bf16 v[118:121], v[146:149], v[174:177], v[118:121]
	v_mfma_f32_16x16x32_bf16 v[110:113], v[154:157], v[174:177], v[110:113]
	v_mfma_f32_16x16x32_bf16 v[102:105], v[146:149], v[196:199], v[102:105]
	v_mfma_f32_16x16x32_bf16 v[94:97], v[154:157], v[196:199], v[94:97]
	v_mfma_f32_16x16x32_bf16 v[86:89], v[146:149], v[204:207], v[86:89]
	v_mfma_f32_16x16x32_bf16 v[78:81], v[154:157], v[204:207], v[78:81]
	v_mfma_f32_16x16x32_bf16 v[70:73], v[146:149], v[212:215], v[70:73]
	v_mfma_f32_16x16x32_bf16 v[66:69], v[154:157], v[212:215], v[66:69]
	v_mfma_f32_16x16x32_bf16 v[118:121], v[150:153], v[192:195], v[118:121]
	v_mfma_f32_16x16x32_bf16 v[110:113], v[158:161], v[192:195], v[110:113]
	v_mfma_f32_16x16x32_bf16 v[102:105], v[150:153], v[200:203], v[102:105]
	v_mfma_f32_16x16x32_bf16 v[94:97], v[158:161], v[200:203], v[94:97]
	s_setprio 2
	s_barrier
; #define PG8_STAGE(bufoff, gbase, voff) do { _Pragma("unroll") for (int _i = 0; _i < 2; ++_i) \
;         __builtin_amdgcn_global_load_lds((const unsigned*)((const char*)(gbase) + (voff)[_i]), (LAS unsigned*)(lds + (bufoff) + ldsw + _i * 8192), 16, 0, 0); } while (0)
; #define PG8_LDA(dst, b, h) do { _Pragma("unroll") for (int m = 0; m < 4; ++m) _Pragma("unroll") for (int k = 0; k < 2; ++k) dst[m][k] = *(const LAS bf16x8*)(lds + PG8_SA(b, h) + aoff + m * 2048 + k * 1024); } while (0)
; #define PG8_MMA(ai, bj, At, Bt) do { __builtin_amdgcn_s_setprio(1); _Pragma("unroll") for (int m = 0; m < 4; ++m) _Pragma("unroll") for (int n = 0; n < 2; ++n) _Pragma("unroll") for (int k = 0; k < 2; ++k) \
;         acc[ai][bj][m][n] = __builtin_amdgcn_mfma_f32_16x16x32_bf16(Bt[n][k], At[m][k], acc[ai][bj][m][n], 0, 0, 0); __builtin_amdgcn_s_setprio(0); } while (0)
; #define PG8_WAIT_V(n) asm volatile("s_waitcnt vmcnt(" #n ")" ::: "memory")
; #define PG8_WAIT_L(n) asm volatile("s_waitcnt lgkmcnt(" #n ")" ::: "memory")
; #define PG8_BAR __builtin_amdgcn_s_barrier()
; #define PG8_SCHED __builtin_amdgcn_sched_barrier(0)
; template <class Epi, class Sched>
; __device__ __forceinline__ void gemm_phase(LAS unsigned char* lds, const Gemm g, Sched S, const Epi& E) {
;     ...
;             PG8_WAIT_V(8); PG8_WAIT_L(0); PG8_BAR; PG8_MMA(0, 0, At, B0); PG8_MMA(0, 1, At, B1); PG8_BAR; PG8_SCHED;
;             PG8_LDA(At, 1, 1); PG8_STAGE(PG8_SB(1, 0), b3, voffB); PG8_STAGE(PG8_SB(1, 1), b3 + hstepB, voffB); PG8_STAGE(PG8_SA(1, 0), a3, voffA);
;             PG8_WAIT_V(8); PG8_WAIT_L(0); PG8_BAR; PG8_MMA(1, 0, At, B0); PG8_MMA(1, 1, At, B1); PG8_BAR; PG8_SCHED;
;         }
;         if (wr == 0) PG8_BAR;
	v_mfma_f32_16x16x32_bf16 v[86:89], v[150:153], v[208:211], v[86:89]
	v_mfma_f32_16x16x32_bf16 v[78:81], v[158:161], v[208:211], v[78:81]
	v_mfma_f32_16x16x32_bf16 v[70:73], v[150:153], v[216:219], v[70:73]
	v_mfma_f32_16x16x32_bf16 v[66:69], v[158:161], v[216:219], v[66:69]
	s_setprio 0
	s_add_i32 s2, s65, s43
	s_add_u32 s100, s76, 0x80
	s_addc_u32 s101, s77, 0
	s_mov_b32 m0, s2
	ds_read_b128 v[174:177], v191 offset:49152
	ds_read_b128 v[192:195], v191 offset:50176
	ds_read_b128 v[196:199], v191 offset:51200
	ds_read_b128 v[200:203], v191 offset:52224
	ds_read_b128 v[204:207], v191 offset:53248
	ds_read_b128 v[208:211], v191 offset:54272
	ds_read_b128 v[212:215], v191 offset:55296
	ds_read_b128 v[216:219], v191 offset:56320
	global_load_lds_dwordx4 v0, s[100:101]
	s_add_i32 m0, s2, 0x2000
	s_add_u32 s2, s76, 0x40080
	s_addc_u32 s3, s77, 0
	s_add_i32 s65, s99, s43
	global_load_lds_dwordx4 v168, s[100:101]
	s_mov_b32 m0, s65
	s_nop 0
	global_load_lds_dwordx4 v0, s[2:3]
	s_add_i32 m0, s65, 0x2000
	s_nop 0
	global_load_lds_dwordx4 v168, s[2:3]
	s_add_u32 s100, vcc_lo, 0x80
	s_addc_u32 s101, vcc_hi, 0
	s_mov_b32 m0, s71
	s_nop 0
	global_load_lds_dwordx4 v164, s[100:101]
	s_mov_b32 m0, s40
	s_nop 0
	global_load_lds_dwordx4 v166, s[100:101]
	s_waitcnt vmcnt(8)
	s_waitcnt lgkmcnt(0)
	s_setprio 1
	s_barrier
	v_mfma_f32_16x16x32_bf16 v[62:65], v[130:133], v[174:177], v[62:65]
	v_mfma_f32_16x16x32_bf16 v[58:61], v[138:141], v[174:177], v[58:61]
	v_mfma_f32_16x16x32_bf16 v[50:53], v[130:133], v[196:199], v[50:53]
	v_mfma_f32_16x16x32_bf16 v[42:45], v[138:141], v[196:199], v[42:45]
	v_mfma_f32_16x16x32_bf16 v[34:37], v[130:133], v[204:207], v[34:37]
	v_mfma_f32_16x16x32_bf16 v[26:29], v[138:141], v[204:207], v[26:29]
	v_mfma_f32_16x16x32_bf16 v[18:21], v[130:133], v[212:215], v[18:21]
	v_mfma_f32_16x16x32_bf16 v[10:13], v[138:141], v[212:215], v[10:13]
	v_mfma_f32_16x16x32_bf16 v[62:65], v[134:137], v[192:195], v[62:65]
	v_mfma_f32_16x16x32_bf16 v[58:61], v[142:145], v[192:195], v[58:61]
	v_mfma_f32_16x16x32_bf16 v[50:53], v[134:137], v[200:203], v[50:53]
	v_mfma_f32_16x16x32_bf16 v[42:45], v[142:145], v[200:203], v[42:45]
	v_mfma_f32_16x16x32_bf16 v[34:37], v[134:137], v[208:211], v[34:37]
	v_mfma_f32_16x16x32_bf16 v[26:29], v[142:145], v[208:211], v[26:29]
	v_mfma_f32_16x16x32_bf16 v[18:21], v[134:137], v[216:219], v[18:21]
	v_mfma_f32_16x16x32_bf16 v[10:13], v[142:145], v[216:219], v[10:13]
	s_setprio 0
	s_setprio 1
	v_mfma_f32_16x16x32_bf16 v[54:57], v[146:149], v[174:177], v[54:57]
	v_mfma_f32_16x16x32_bf16 v[46:49], v[154:157], v[174:177], v[46:49]
	v_mfma_f32_16x16x32_bf16 v[38:41], v[146:149], v[196:199], v[38:41]
	v_mfma_f32_16x16x32_bf16 v[30:33], v[154:157], v[196:199], v[30:33]
	v_mfma_f32_16x16x32_bf16 v[22:25], v[146:149], v[204:207], v[22:25]
	v_mfma_f32_16x16x32_bf16 v[14:17], v[154:157], v[204:207], v[14:17]
	v_mfma_f32_16x16x32_bf16 v[6:9], v[146:149], v[212:215], v[6:9]
	v_mfma_f32_16x16x32_bf16 v[2:5], v[154:157], v[212:215], v[2:5]
	v_mfma_f32_16x16x32_bf16 v[54:57], v[150:153], v[192:195], v[54:57]
	v_mfma_f32_16x16x32_bf16 v[46:49], v[158:161], v[192:195], v[46:49]
	v_mfma_f32_16x16x32_bf16 v[38:41], v[150:153], v[200:203], v[38:41]
	v_mfma_f32_16x16x32_bf16 v[30:33], v[158:161], v[200:203], v[30:33]
	s_setprio 2
	s_barrier
	v_mfma_f32_16x16x32_bf16 v[22:25], v[150:153], v[208:211], v[22:25]
	v_mfma_f32_16x16x32_bf16 v[14:17], v[158:161], v[208:211], v[14:17]
	v_mfma_f32_16x16x32_bf16 v[6:9], v[150:153], v[216:219], v[6:9]
	v_mfma_f32_16x16x32_bf16 v[2:5], v[158:161], v[216:219], v[2:5]
	s_setprio 0
	s_add_u32 s63, s63, 0x100
	s_addc_u32 s64, s64, 0
	s_add_u32 s0, s0, 0x100
	s_addc_u32 s1, s1, 0
	s_cmp_ge_u32 s67, s58
	s_mov_b32 s65, s67
	s_cbranch_scc0 .LBB0_630
	s_and_b64 vcc, exec, s[94:95]
	s_cbranch_vccz .LBB0_635
	s_barrier
	s_and_b64 s[0:1], s[96:97], s[10:11]
	s_andn2_b64 vcc, exec, s[0:1]
	s_mov_b64 s[0:1], -1
	s_cbranch_vccnz .LBB0_636

; #define PG8_STAGE(bufoff, gbase, voff) do { _Pragma("unroll") for (int _i = 0; _i < 2; ++_i) \
;         __builtin_amdgcn_global_load_lds((const unsigned*)((const char*)(gbase) + (voff)[_i]), (LAS unsigned*)(lds + (bufoff) + ldsw + _i * 8192), 16, 0, 0); } while (0)
; #define PG8_LDA(dst, b, h) do { _Pragma("unroll") for (int m = 0; m < 4; ++m) _Pragma("unroll") for (int k = 0; k < 2; ++k) dst[m][k] = *(const LAS bf16x8*)(lds + PG8_SA(b, h) + aoff + m * 2048 + k * 1024); } while (0)
; #define PG8_LDB(dst, b, h) do { _Pragma("unroll") for (int n = 0; n < 2; ++n) _Pragma("unroll") for (int k = 0; k < 2; ++k) dst[n][k] = *(const LAS bf16x8*)(lds + PG8_SB(b, h) + boff + n * 2048 + k * 1024); } while (0)
; #define PG8_MMA(ai, bj, At, Bt) do { __builtin_amdgcn_s_setprio(1); _Pragma("unroll") for (int m = 0; m < 4; ++m) _Pragma("unroll") for (int n = 0; n < 2; ++n) _Pragma("unroll") for (int k = 0; k < 2; ++k) \
;         acc[ai][bj][m][n] = __builtin_amdgcn_mfma_f32_16x16x32_bf16(Bt[n][k], At[m][k], acc[ai][bj][m][n], 0, 0, 0); __builtin_amdgcn_s_setprio(0); } while (0)
; #define PG8_WAIT_V(n) asm volatile("s_waitcnt vmcnt(" #n ")" ::: "memory")
; template <class Epi, class Sched>
; __device__ __forceinline__ void gemm_phase(LAS unsigned char* lds, const Gemm g, Sched S, const Epi& E) {
;     ...
;             const bool last = (t == nt - 2);
;             const char* a1 = cA + (size_t)(t + 1) * kstep;
;             const char* a2 = last ? nA : cA + (size_t)(t + 2) * kstep; const char* b2 = last ? nB : cB + (size_t)(t + 2) * kstep;
;             const char* a3 = a2 + kstep; const char* b3 = b2 + kstep;
;             PG8_LDB(B0, 0, 0); PG8_LDB(B1, 0, 1); PG8_SCHED; PG8_LDA(At, 0, 0); PG8_STAGE(PG8_SA(1, 1), a1 + hstepA, voffA);
;             PG8_WAIT_V(8); PG8_WAIT_L(0); PG8_BAR; PG8_MMA(0, 0, At, B0); PG8_MMA(0, 1, At, B1); PG8_BAR; PG8_SCHED;
;             PG8_LDA(At, 0, 1); PG8_STAGE(PG8_SB(0, 0), b2, voffB); PG8_STAGE(PG8_SB(0, 1), b2 + hstepB, voffB); PG8_STAGE(PG8_SA(0, 0), a2, voffA);
;             PG8_WAIT_V(8); PG8_WAIT_L(0); PG8_BAR; PG8_MMA(1, 0, At, B0); PG8_MMA(1, 1, At, B1); PG8_BAR; PG8_SCHED;
;             PG8_LDB(B0, 1, 0); PG8_LDB(B1, 1, 1); PG8_SCHED; PG8_LDA(At, 1, 0); PG8_STAGE(PG8_SA(0, 1), a2 + hstepA, voffA);
;             PG8_WAIT_V(8); PG8_WAIT_L(0); PG8_BAR; PG8_MMA(0, 0, At, B0); PG8_MMA(0, 1, At, B1); PG8_BAR; PG8_SCHED;
.LBB0_727:
	s_add_i32 s21, s20, 2
	s_add_u32 s3, s42, 0x80
	s_addc_u32 s35, s43, 0
	s_add_i32 s52, 0, 0x10000
	s_cmp_eq_u32 s99, s20
	s_cselect_b32 s45, s89, s35
	s_cselect_b32 s44, s88, s3
	s_cselect_b32 s41, s91, s19
	s_cselect_b32 s40, s90, s11
	s_add_i32 s3, 0, 0x14000
	v_add_u32_e32 v126, s52, v192
	v_add_u32_e32 v170, s3, v192
	ds_read_b128 v[114:117], v126
	ds_read_b128 v[118:121], v126 offset:1024
	ds_read_b128 v[122:125], v126 offset:2048
	ds_read_b128 v[126:129], v126 offset:3072
	ds_read_b128 v[130:133], v170
	ds_read_b128 v[134:137], v170 offset:1024
	ds_read_b128 v[166:169], v170 offset:2048
	ds_read_b128 v[170:173], v170 offset:3072
	s_add_i32 m0, s85, 0xc000
	ds_read_b128 v[174:177], v194
	ds_read_b128 v[178:181], v194 offset:1024
	ds_read_b128 v[196:199], v194 offset:2048
	ds_read_b128 v[200:203], v194 offset:3072
	ds_read_b128 v[204:207], v194 offset:4096
	ds_read_b128 v[208:211], v194 offset:5120
	ds_read_b128 v[212:215], v194 offset:6144
	ds_read_b128 v[216:219], v194 offset:7168
	global_load_lds_dwordx4 v164, s[42:43]
	s_add_i32 m0, s85, 0xe000
	s_nop 0
	global_load_lds_dwordx4 v160, s[42:43]
	s_waitcnt vmcnt(8)
	s_waitcnt lgkmcnt(0)
	s_setprio 1
	s_barrier
	v_mfma_f32_16x16x32_bf16 v[150:153], v[114:117], v[174:177], v[150:153]
	v_mfma_f32_16x16x32_bf16 v[146:149], v[122:125], v[174:177], v[146:149]
	v_mfma_f32_16x16x32_bf16 v[110:113], v[114:117], v[196:199], v[110:113]
	v_mfma_f32_16x16x32_bf16 v[106:109], v[122:125], v[196:199], v[106:109]
	v_mfma_f32_16x16x32_bf16 v[94:97], v[114:117], v[204:207], v[94:97]
	v_mfma_f32_16x16x32_bf16 v[90:93], v[122:125], v[204:207], v[90:93]
	v_mfma_f32_16x16x32_bf16 v[78:81], v[114:117], v[212:215], v[78:81]
	v_mfma_f32_16x16x32_bf16 v[74:77], v[122:125], v[212:215], v[74:77]
	v_mfma_f32_16x16x32_bf16 v[150:153], v[118:121], v[178:181], v[150:153]
	v_mfma_f32_16x16x32_bf16 v[146:149], v[126:129], v[178:181], v[146:149]
	v_mfma_f32_16x16x32_bf16 v[110:113], v[118:121], v[200:203], v[110:113]
	v_mfma_f32_16x16x32_bf16 v[106:109], v[126:129], v[200:203], v[106:109]
	v_mfma_f32_16x16x32_bf16 v[94:97], v[118:121], v[208:211], v[94:97]
	v_mfma_f32_16x16x32_bf16 v[90:93], v[126:129], v[208:211], v[90:93]
	v_mfma_f32_16x16x32_bf16 v[78:81], v[118:121], v[216:219], v[78:81]
	v_mfma_f32_16x16x32_bf16 v[74:77], v[126:129], v[216:219], v[74:77]
	s_setprio 0
	s_setprio 1
	v_mfma_f32_16x16x32_bf16 v[142:145], v[130:133], v[174:177], v[142:145]
	v_mfma_f32_16x16x32_bf16 v[138:141], v[166:169], v[174:177], v[138:141]
	v_mfma_f32_16x16x32_bf16 v[102:105], v[130:133], v[196:199], v[102:105]
	v_mfma_f32_16x16x32_bf16 v[98:101], v[166:169], v[196:199], v[98:101]
	v_mfma_f32_16x16x32_bf16 v[86:89], v[130:133], v[204:207], v[86:89]
	v_mfma_f32_16x16x32_bf16 v[82:85], v[166:169], v[204:207], v[82:85]
	v_mfma_f32_16x16x32_bf16 v[70:73], v[130:133], v[212:215], v[70:73]
	v_mfma_f32_16x16x32_bf16 v[66:69], v[166:169], v[212:215], v[66:69]
	v_mfma_f32_16x16x32_bf16 v[142:145], v[134:137], v[178:181], v[142:145]
	v_mfma_f32_16x16x32_bf16 v[138:141], v[170:173], v[178:181], v[138:141]
	v_mfma_f32_16x16x32_bf16 v[102:105], v[134:137], v[200:203], v[102:105]
	v_mfma_f32_16x16x32_bf16 v[98:101], v[170:173], v[200:203], v[98:101]
	s_setprio 2
	s_barrier
	v_mfma_f32_16x16x32_bf16 v[86:89], v[134:137], v[208:211], v[86:89]
	v_mfma_f32_16x16x32_bf16 v[82:85], v[170:173], v[208:211], v[82:85]
	v_mfma_f32_16x16x32_bf16 v[70:73], v[134:137], v[216:219], v[70:73]
	v_mfma_f32_16x16x32_bf16 v[66:69], v[170:173], v[216:219], v[66:69]
	s_setprio 0
	s_add_i32 s20, s52, s77
	s_add_u32 s100, s40, 0x80
	s_addc_u32 s101, s41, 0
	s_mov_b32 m0, s20
	ds_read_b128 v[174:177], v194 offset:16384
	ds_read_b128 v[178:181], v194 offset:17408
	ds_read_b128 v[196:199], v194 offset:18432
	ds_read_b128 v[200:203], v194 offset:19456
	ds_read_b128 v[204:207], v194 offset:20480
	ds_read_b128 v[208:211], v194 offset:21504
	ds_read_b128 v[212:215], v194 offset:22528
	ds_read_b128 v[216:219], v194 offset:23552
	global_load_lds_dwordx4 v0, s[40:41]
	s_add_i32 m0, s20, 0x2000
	s_add_i32 s3, s3, s77
	global_load_lds_dwordx4 v158, s[40:41]
	s_add_u32 s40, s40, s24
	s_addc_u32 s41, s41, s25
	s_mov_b32 m0, s3
	s_nop 0
	global_load_lds_dwordx4 v0, s[40:41]
	s_add_i32 m0, s3, 0x2000
	s_nop 0
	global_load_lds_dwordx4 v158, s[40:41]
	s_mov_b32 m0, s85
	s_nop 0
	global_load_lds_dwordx4 v154, s[44:45]
	s_mov_b32 m0, s92
	s_nop 0
	global_load_lds_dwordx4 v156, s[44:45]
	s_waitcnt vmcnt(8)
	s_waitcnt lgkmcnt(0)
	s_setprio 1
	s_barrier
	v_mfma_f32_16x16x32_bf16 v[62:65], v[114:117], v[174:177], v[62:65]
	v_mfma_f32_16x16x32_bf16 v[58:61], v[122:125], v[174:177], v[58:61]
	v_mfma_f32_16x16x32_bf16 v[46:49], v[114:117], v[196:199], v[46:49]
	v_mfma_f32_16x16x32_bf16 v[42:45], v[122:125], v[196:199], v[42:45]
	v_mfma_f32_16x16x32_bf16 v[30:33], v[114:117], v[204:207], v[30:33]
	v_mfma_f32_16x16x32_bf16 v[26:29], v[122:125], v[204:207], v[26:29]
	v_mfma_f32_16x16x32_bf16 v[14:17], v[114:117], v[212:215], v[14:17]
	v_mfma_f32_16x16x32_bf16 v[10:13], v[122:125], v[212:215], v[10:13]
	v_mfma_f32_16x16x32_bf16 v[62:65], v[118:121], v[178:181], v[62:65]
	v_mfma_f32_16x16x32_bf16 v[58:61], v[126:129], v[178:181], v[58:61]
	v_mfma_f32_16x16x32_bf16 v[46:49], v[118:121], v[200:203], v[46:49]
	v_mfma_f32_16x16x32_bf16 v[42:45], v[126:129], v[200:203], v[42:45]
	v_mfma_f32_16x16x32_bf16 v[30:33], v[118:121], v[208:211], v[30:33]
	v_mfma_f32_16x16x32_bf16 v[26:29], v[126:129], v[208:211], v[26:29]
	v_mfma_f32_16x16x32_bf16 v[14:17], v[118:121], v[216:219], v[14:17]
	v_mfma_f32_16x16x32_bf16 v[10:13], v[126:129], v[216:219], v[10:13]
	s_setprio 0
	s_setprio 1
	v_mfma_f32_16x16x32_bf16 v[54:57], v[130:133], v[174:177], v[54:57]
	v_mfma_f32_16x16x32_bf16 v[50:53], v[166:169], v[174:177], v[50:53]
	v_mfma_f32_16x16x32_bf16 v[38:41], v[130:133], v[196:199], v[38:41]
	v_mfma_f32_16x16x32_bf16 v[34:37], v[166:169], v[196:199], v[34:37]
	v_mfma_f32_16x16x32_bf16 v[22:25], v[130:133], v[204:207], v[22:25]
	v_mfma_f32_16x16x32_bf16 v[18:21], v[166:169], v[204:207], v[18:21]
	v_mfma_f32_16x16x32_bf16 v[6:9], v[130:133], v[212:215], v[6:9]
	v_mfma_f32_16x16x32_bf16 v[2:5], v[166:169], v[212:215], v[2:5]
	v_mfma_f32_16x16x32_bf16 v[54:57], v[134:137], v[178:181], v[54:57]
	v_mfma_f32_16x16x32_bf16 v[50:53], v[170:173], v[178:181], v[50:53]
	v_mfma_f32_16x16x32_bf16 v[38:41], v[134:137], v[200:203], v[38:41]
	v_mfma_f32_16x16x32_bf16 v[34:37], v[170:173], v[200:203], v[34:37]
	s_setprio 2
	s_barrier
; #define PG8_STAGE(bufoff, gbase, voff) do { _Pragma("unroll") for (int _i = 0; _i < 2; ++_i) \
;         __builtin_amdgcn_global_load_lds((const unsigned*)((const char*)(gbase) + (voff)[_i]), (LAS unsigned*)(lds + (bufoff) + ldsw + _i * 8192), 16, 0, 0); } while (0)
; #define PG8_LDA(dst, b, h) do { _Pragma("unroll") for (int m = 0; m < 4; ++m) _Pragma("unroll") for (int k = 0; k < 2; ++k) dst[m][k] = *(const LAS bf16x8*)(lds + PG8_SA(b, h) + aoff + m * 2048 + k * 1024); } while (0)
; #define PG8_LDB(dst, b, h) do { _Pragma("unroll") for (int n = 0; n < 2; ++n) _Pragma("unroll") for (int k = 0; k < 2; ++k) dst[n][k] = *(const LAS bf16x8*)(lds + PG8_SB(b, h) + boff + n * 2048 + k * 1024); } while (0)
; #define PG8_MMA(ai, bj, At, Bt) do { __builtin_amdgcn_s_setprio(1); _Pragma("unroll") for (int m = 0; m < 4; ++m) _Pragma("unroll") for (int n = 0; n < 2; ++n) _Pragma("unroll") for (int k = 0; k < 2; ++k) \
;         acc[ai][bj][m][n] = __builtin_amdgcn_mfma_f32_16x16x32_bf16(Bt[n][k], At[m][k], acc[ai][bj][m][n], 0, 0, 0); __builtin_amdgcn_s_setprio(0); } while (0)
; #define PG8_WAIT_V(n) asm volatile("s_waitcnt vmcnt(" #n ")" ::: "memory")
; #define PG8_WAIT_L(n) asm volatile("s_waitcnt lgkmcnt(" #n ")" ::: "memory")
; #define PG8_BAR __builtin_amdgcn_s_barrier()
; #define PG8_SCHED __builtin_amdgcn_sched_barrier(0)
; template <class Epi, class Sched>
; __device__ __forceinline__ void gemm_phase(LAS unsigned char* lds, const Gemm g, Sched S, const Epi& E) {
;     ...
;             PG8_WAIT_V(8); PG8_WAIT_L(0); PG8_BAR; PG8_MMA(1, 0, At, B0); PG8_MMA(1, 1, At, B1); PG8_BAR; PG8_SCHED;
;             PG8_LDB(B0, 1, 0); PG8_LDB(B1, 1, 1); PG8_SCHED; PG8_LDA(At, 1, 0); PG8_STAGE(PG8_SA(0, 1), a2 + hstepA, voffA);
;             PG8_WAIT_V(8); PG8_WAIT_L(0); PG8_BAR; PG8_MMA(0, 0, At, B0); PG8_MMA(0, 1, At, B1); PG8_BAR; PG8_SCHED;
	v_mfma_f32_16x16x32_bf16 v[22:25], v[134:137], v[208:211], v[22:25]
	v_mfma_f32_16x16x32_bf16 v[18:21], v[170:173], v[208:211], v[18:21]
	v_mfma_f32_16x16x32_bf16 v[6:9], v[134:137], v[216:219], v[6:9]
	v_mfma_f32_16x16x32_bf16 v[2:5], v[170:173], v[216:219], v[2:5]
	s_setprio 0
	s_add_i32 s3, 0, 0x18000
	s_add_i32 s20, 0, 0x1c000
	v_add_u32_e32 v126, s3, v192
	v_add_u32_e32 v170, s20, v192
	ds_read_b128 v[114:117], v126
	ds_read_b128 v[118:121], v126 offset:1024
	ds_read_b128 v[122:125], v126 offset:2048
	ds_read_b128 v[126:129], v126 offset:3072
	ds_read_b128 v[130:133], v170
	ds_read_b128 v[134:137], v170 offset:1024
	ds_read_b128 v[166:169], v170 offset:2048
	ds_read_b128 v[170:173], v170 offset:3072
	s_add_u32 s40, s44, s8
	s_addc_u32 s41, s45, 0
	s_mov_b32 m0, s93
	ds_read_b128 v[174:177], v194 offset:32768
	ds_read_b128 v[178:181], v194 offset:33792
	ds_read_b128 v[196:199], v194 offset:34816
	ds_read_b128 v[200:203], v194 offset:35840
	ds_read_b128 v[204:207], v194 offset:36864
	ds_read_b128 v[208:211], v194 offset:37888
	ds_read_b128 v[212:215], v194 offset:38912
	ds_read_b128 v[216:219], v194 offset:39936
	global_load_lds_dwordx4 v154, s[40:41]
	s_mov_b32 m0, s94
	s_nop 0
	global_load_lds_dwordx4 v156, s[40:41]
	s_waitcnt vmcnt(8)
	s_waitcnt lgkmcnt(0)
	s_setprio 1
	s_barrier
	v_mfma_f32_16x16x32_bf16 v[150:153], v[114:117], v[174:177], v[150:153]
	v_mfma_f32_16x16x32_bf16 v[146:149], v[122:125], v[174:177], v[146:149]
	v_mfma_f32_16x16x32_bf16 v[110:113], v[114:117], v[196:199], v[110:113]
	v_mfma_f32_16x16x32_bf16 v[106:109], v[122:125], v[196:199], v[106:109]
	v_mfma_f32_16x16x32_bf16 v[94:97], v[114:117], v[204:207], v[94:97]
	v_mfma_f32_16x16x32_bf16 v[90:93], v[122:125], v[204:207], v[90:93]
	v_mfma_f32_16x16x32_bf16 v[78:81], v[114:117], v[212:215], v[78:81]
	v_mfma_f32_16x16x32_bf16 v[74:77], v[122:125], v[212:215], v[74:77]
	v_mfma_f32_16x16x32_bf16 v[150:153], v[118:121], v[178:181], v[150:153]
	v_mfma_f32_16x16x32_bf16 v[146:149], v[126:129], v[178:181], v[146:149]
	v_mfma_f32_16x16x32_bf16 v[110:113], v[118:121], v[200:203], v[110:113]
	v_mfma_f32_16x16x32_bf16 v[106:109], v[126:129], v[200:203], v[106:109]
	v_mfma_f32_16x16x32_bf16 v[94:97], v[118:121], v[208:211], v[94:97]
	v_mfma_f32_16x16x32_bf16 v[90:93], v[126:129], v[208:211], v[90:93]
	v_mfma_f32_16x16x32_bf16 v[78:81], v[118:121], v[216:219], v[78:81]
	v_mfma_f32_16x16x32_bf16 v[74:77], v[126:129], v[216:219], v[74:77]
	s_setprio 0
	s_setprio 1
	v_mfma_f32_16x16x32_bf16 v[142:145], v[130:133], v[174:177], v[142:145]
	v_mfma_f32_16x16x32_bf16 v[138:141], v[166:169], v[174:177], v[138:141]
	v_mfma_f32_16x16x32_bf16 v[102:105], v[130:133], v[196:199], v[102:105]
	v_mfma_f32_16x16x32_bf16 v[98:101], v[166:169], v[196:199], v[98:101]
	v_mfma_f32_16x16x32_bf16 v[86:89], v[130:133], v[204:207], v[86:89]
	v_mfma_f32_16x16x32_bf16 v[82:85], v[166:169], v[204:207], v[82:85]
	v_mfma_f32_16x16x32_bf16 v[70:73], v[130:133], v[212:215], v[70:73]
	v_mfma_f32_16x16x32_bf16 v[66:69], v[166:169], v[212:215], v[66:69]
	v_mfma_f32_16x16x32_bf16 v[142:145], v[134:137], v[178:181], v[142:145]
	v_mfma_f32_16x16x32_bf16 v[138:141], v[170:173], v[178:181], v[138:141]
	v_mfma_f32_16x16x32_bf16 v[102:105], v[134:137], v[200:203], v[102:105]
	v_mfma_f32_16x16x32_bf16 v[98:101], v[170:173], v[200:203], v[98:101]
	s_setprio 2
	s_barrier
; #define PG8_STAGE(bufoff, gbase, voff) do { _Pragma("unroll") for (int _i = 0; _i < 2; ++_i) \
;         __builtin_amdgcn_global_load_lds((const unsigned*)((const char*)(gbase) + (voff)[_i]), (LAS unsigned*)(lds + (bufoff) + ldsw + _i * 8192), 16, 0, 0); } while (0)
; #define PG8_LDA(dst, b, h) do { _Pragma("unroll") for (int m = 0; m < 4; ++m) _Pragma("unroll") for (int k = 0; k < 2; ++k) dst[m][k] = *(const LAS bf16x8*)(lds + PG8_SA(b, h) + aoff + m * 2048 + k * 1024); } while (0)
; #define PG8_MMA(ai, bj, At, Bt) do { __builtin_amdgcn_s_setprio(1); _Pragma("unroll") for (int m = 0; m < 4; ++m) _Pragma("unroll") for (int n = 0; n < 2; ++n) _Pragma("unroll") for (int k = 0; k < 2; ++k) \
;         acc[ai][bj][m][n] = __builtin_amdgcn_mfma_f32_16x16x32_bf16(Bt[n][k], At[m][k], acc[ai][bj][m][n], 0, 0, 0); __builtin_amdgcn_s_setprio(0); } while (0)
; #define PG8_WAIT_V(n) asm volatile("s_waitcnt vmcnt(" #n ")" ::: "memory")
; #define PG8_WAIT_L(n) asm volatile("s_waitcnt lgkmcnt(" #n ")" ::: "memory")
; #define PG8_BAR __builtin_amdgcn_s_barrier()
; #define PG8_SCHED __builtin_amdgcn_sched_barrier(0)
; template <class Epi, class Sched>
; __device__ __forceinline__ void gemm_phase(LAS unsigned char* lds, const Gemm g, Sched S, const Epi& E) {
;     ...
;             PG8_WAIT_V(8); PG8_WAIT_L(0); PG8_BAR; PG8_MMA(0, 0, At, B0); PG8_MMA(0, 1, At, B1); PG8_BAR; PG8_SCHED;
;             PG8_LDA(At, 1, 1); PG8_STAGE(PG8_SB(1, 0), b3, voffB); PG8_STAGE(PG8_SB(1, 1), b3 + hstepB, voffB); PG8_STAGE(PG8_SA(1, 0), a3, voffA);
;             PG8_WAIT_V(8); PG8_WAIT_L(0); PG8_BAR; PG8_MMA(1, 0, At, B0); PG8_MMA(1, 1, At, B1); PG8_BAR; PG8_SCHED;
;         }
;         if (wr == 0) PG8_BAR;
	v_mfma_f32_16x16x32_bf16 v[86:89], v[134:137], v[208:211], v[86:89]
	v_mfma_f32_16x16x32_bf16 v[82:85], v[170:173], v[208:211], v[82:85]
	v_mfma_f32_16x16x32_bf16 v[70:73], v[134:137], v[216:219], v[70:73]
	v_mfma_f32_16x16x32_bf16 v[66:69], v[170:173], v[216:219], v[66:69]
	s_setprio 0
	s_add_i32 s3, s3, s77
	s_mov_b32 m0, s3
	ds_read_b128 v[174:177], v194 offset:49152
	ds_read_b128 v[178:181], v194 offset:50176
	ds_read_b128 v[196:199], v194 offset:51200
	ds_read_b128 v[200:203], v194 offset:52224
	ds_read_b128 v[204:207], v194 offset:53248
	ds_read_b128 v[208:211], v194 offset:54272
	ds_read_b128 v[212:215], v194 offset:55296
	ds_read_b128 v[216:219], v194 offset:56320
	global_load_lds_dwordx4 v0, s[100:101]
	s_add_i32 m0, s3, 0x2000
	s_add_i32 s3, s20, s77
	global_load_lds_dwordx4 v158, s[100:101]
	s_add_u32 s100, s100, s24
	s_addc_u32 s101, s101, s25
	s_mov_b32 m0, s3
	s_nop 0
	global_load_lds_dwordx4 v0, s[100:101]
	s_add_i32 m0, s3, 0x2000
	s_nop 0
	global_load_lds_dwordx4 v158, s[100:101]
	s_add_u32 s100, s44, 0x80
	s_addc_u32 s101, s45, 0
	s_mov_b32 m0, s97
	s_nop 0
	global_load_lds_dwordx4 v154, s[100:101]
	s_mov_b32 m0, s98
	s_nop 0
	global_load_lds_dwordx4 v156, s[100:101]
	s_waitcnt vmcnt(8)
	s_waitcnt lgkmcnt(0)
	s_setprio 1
	s_barrier
	v_mfma_f32_16x16x32_bf16 v[62:65], v[114:117], v[174:177], v[62:65]
	v_mfma_f32_16x16x32_bf16 v[58:61], v[122:125], v[174:177], v[58:61]
	v_mfma_f32_16x16x32_bf16 v[46:49], v[114:117], v[196:199], v[46:49]
	v_mfma_f32_16x16x32_bf16 v[42:45], v[122:125], v[196:199], v[42:45]
	v_mfma_f32_16x16x32_bf16 v[30:33], v[114:117], v[204:207], v[30:33]
	v_mfma_f32_16x16x32_bf16 v[26:29], v[122:125], v[204:207], v[26:29]
	v_mfma_f32_16x16x32_bf16 v[14:17], v[114:117], v[212:215], v[14:17]
	v_mfma_f32_16x16x32_bf16 v[10:13], v[122:125], v[212:215], v[10:13]
	v_mfma_f32_16x16x32_bf16 v[62:65], v[118:121], v[178:181], v[62:65]
	v_mfma_f32_16x16x32_bf16 v[58:61], v[126:129], v[178:181], v[58:61]
	v_mfma_f32_16x16x32_bf16 v[46:49], v[118:121], v[200:203], v[46:49]
	v_mfma_f32_16x16x32_bf16 v[42:45], v[126:129], v[200:203], v[42:45]
	v_mfma_f32_16x16x32_bf16 v[30:33], v[118:121], v[208:211], v[30:33]
	v_mfma_f32_16x16x32_bf16 v[26:29], v[126:129], v[208:211], v[26:29]
	v_mfma_f32_16x16x32_bf16 v[14:17], v[118:121], v[216:219], v[14:17]
	v_mfma_f32_16x16x32_bf16 v[10:13], v[126:129], v[216:219], v[10:13]
	s_setprio 0
	s_setprio 1
	v_mfma_f32_16x16x32_bf16 v[54:57], v[130:133], v[174:177], v[54:57]
	v_mfma_f32_16x16x32_bf16 v[50:53], v[166:169], v[174:177], v[50:53]
	v_mfma_f32_16x16x32_bf16 v[38:41], v[130:133], v[196:199], v[38:41]
	v_mfma_f32_16x16x32_bf16 v[34:37], v[166:169], v[196:199], v[34:37]
	v_mfma_f32_16x16x32_bf16 v[22:25], v[130:133], v[204:207], v[22:25]
	v_mfma_f32_16x16x32_bf16 v[18:21], v[166:169], v[204:207], v[18:21]
	v_mfma_f32_16x16x32_bf16 v[6:9], v[130:133], v[212:215], v[6:9]
	v_mfma_f32_16x16x32_bf16 v[2:5], v[166:169], v[212:215], v[2:5]
	v_mfma_f32_16x16x32_bf16 v[54:57], v[134:137], v[178:181], v[54:57]
	v_mfma_f32_16x16x32_bf16 v[50:53], v[170:173], v[178:181], v[50:53]
	v_mfma_f32_16x16x32_bf16 v[38:41], v[134:137], v[200:203], v[38:41]
	v_mfma_f32_16x16x32_bf16 v[34:37], v[170:173], v[200:203], v[34:37]
	s_setprio 2
	s_barrier
	v_mfma_f32_16x16x32_bf16 v[22:25], v[134:137], v[208:211], v[22:25]
	v_mfma_f32_16x16x32_bf16 v[18:21], v[170:173], v[208:211], v[18:21]
	v_mfma_f32_16x16x32_bf16 v[6:9], v[134:137], v[216:219], v[6:9]
	v_mfma_f32_16x16x32_bf16 v[2:5], v[170:173], v[216:219], v[2:5]
	s_setprio 0
	s_add_u32 s11, s11, 0x100
	s_addc_u32 s19, s19, 0
	s_add_u32 s42, s42, 0x100
	s_addc_u32 s43, s43, 0
	s_cmp_ge_u32 s21, s96
	s_mov_b32 s20, s21
	s_cbranch_scc0 .LBB0_727
	s_and_b64 vcc, exec, s[30:31]
	s_cbranch_vccz .LBB0_730
	s_barrier

; #define PG8_STAGE(bufoff, gbase, voff) do { _Pragma("unroll") for (int _i = 0; _i < 2; ++_i) \
;         __builtin_amdgcn_global_load_lds((const unsigned*)((const char*)(gbase) + (voff)[_i]), (LAS unsigned*)(lds + (bufoff) + ldsw + _i * 8192), 16, 0, 0); } while (0)
; #define PG8_LDA(dst, b, h) do { _Pragma("unroll") for (int m = 0; m < 4; ++m) _Pragma("unroll") for (int k = 0; k < 2; ++k) dst[m][k] = *(const LAS bf16x8*)(lds + PG8_SA(b, h) + aoff + m * 2048 + k * 1024); } while (0)
; #define PG8_LDB(dst, b, h) do { _Pragma("unroll") for (int n = 0; n < 2; ++n) _Pragma("unroll") for (int k = 0; k < 2; ++k) dst[n][k] = *(const LAS bf16x8*)(lds + PG8_SB(b, h) + boff + n * 2048 + k * 1024); } while (0)
; #define PG8_MMA(ai, bj, At, Bt) do { __builtin_amdgcn_s_setprio(1); _Pragma("unroll") for (int m = 0; m < 4; ++m) _Pragma("unroll") for (int n = 0; n < 2; ++n) _Pragma("unroll") for (int k = 0; k < 2; ++k) \
;         acc[ai][bj][m][n] = __builtin_amdgcn_mfma_f32_16x16x32_bf16(Bt[n][k], At[m][k], acc[ai][bj][m][n], 0, 0, 0); __builtin_amdgcn_s_setprio(0); } while (0)
; #define PG8_WAIT_V(n) asm volatile("s_waitcnt vmcnt(" #n ")" ::: "memory")
; template <class Epi, class Sched>
; __device__ __forceinline__ void gemm_phase(LAS unsigned char* lds, const Gemm g, Sched S, const Epi& E) {
;     ...
;             const bool last = (t == nt - 2);
;             const char* a1 = cA + (size_t)(t + 1) * kstep;
;             const char* a2 = last ? nA : cA + (size_t)(t + 2) * kstep; const char* b2 = last ? nB : cB + (size_t)(t + 2) * kstep;
;             const char* a3 = a2 + kstep; const char* b3 = b2 + kstep;
;             PG8_LDB(B0, 0, 0); PG8_LDB(B1, 0, 1); PG8_SCHED; PG8_LDA(At, 0, 0); PG8_STAGE(PG8_SA(1, 1), a1 + hstepA, voffA);
;             PG8_WAIT_V(8); PG8_WAIT_L(0); PG8_BAR; PG8_MMA(0, 0, At, B0); PG8_MMA(0, 1, At, B1); PG8_BAR; PG8_SCHED;
;             PG8_LDA(At, 0, 1); PG8_STAGE(PG8_SB(0, 0), b2, voffB); PG8_STAGE(PG8_SB(0, 1), b2 + hstepB, voffB); PG8_STAGE(PG8_SA(0, 0), a2, voffA);
;             PG8_WAIT_V(8); PG8_WAIT_L(0); PG8_BAR; PG8_MMA(1, 0, At, B0); PG8_MMA(1, 1, At, B1); PG8_BAR; PG8_SCHED;
;             PG8_LDB(B0, 1, 0); PG8_LDB(B1, 1, 1); PG8_SCHED; PG8_LDA(At, 1, 0); PG8_STAGE(PG8_SA(0, 1), a2 + hstepA, voffA);
;             PG8_WAIT_V(8); PG8_WAIT_L(0); PG8_BAR; PG8_MMA(0, 0, At, B0); PG8_MMA(0, 1, At, B1); PG8_BAR; PG8_SCHED;
.LBB0_770:
	s_add_u32 s3, s10, 0xfffc0080
	s_addc_u32 s42, s11, -1
	s_add_i32 s71, 0, 0x10000
	s_cmp_eq_u32 s70, 12
	s_cselect_b32 s45, s60, s42
	s_cselect_b32 s44, s61, s3
	s_cselect_b32 s43, s62, s65
	s_cselect_b32 s42, s63, s64
	s_add_i32 s3, 0, 0x14000
	v_add_u32_e32 v142, s71, v183
	v_add_u32_e32 v158, s3, v183
	ds_read_b128 v[130:133], v142
	ds_read_b128 v[134:137], v142 offset:1024
	ds_read_b128 v[138:141], v142 offset:2048
	ds_read_b128 v[142:145], v142 offset:3072
	ds_read_b128 v[146:149], v158
	ds_read_b128 v[150:153], v158 offset:1024
	ds_read_b128 v[154:157], v158 offset:2048
	ds_read_b128 v[158:161], v158 offset:3072
	s_add_i32 m0, s9, 0xc000
	ds_read_b128 v[174:177], v194
	ds_read_b128 v[196:199], v194 offset:1024
	ds_read_b128 v[200:203], v194 offset:2048
	ds_read_b128 v[204:207], v194 offset:3072
	ds_read_b128 v[208:211], v194 offset:4096
	ds_read_b128 v[212:215], v194 offset:5120
	ds_read_b128 v[216:219], v194 offset:6144
	ds_read_b128 v[220:223], v194 offset:7168
	global_load_lds_dwordx4 v172, s[10:11]
	s_add_i32 m0, s9, 0xe000
	s_nop 0
	global_load_lds_dwordx4 v170, s[10:11]
	s_waitcnt vmcnt(8)
	s_waitcnt lgkmcnt(0)
	s_setprio 1
	s_barrier
	v_mfma_f32_16x16x32_bf16 v[126:129], v[130:133], v[174:177], v[126:129]
	v_mfma_f32_16x16x32_bf16 v[118:121], v[138:141], v[174:177], v[118:121]
	v_mfma_f32_16x16x32_bf16 v[110:113], v[130:133], v[200:203], v[110:113]
	v_mfma_f32_16x16x32_bf16 v[102:105], v[138:141], v[200:203], v[102:105]
	v_mfma_f32_16x16x32_bf16 v[94:97], v[130:133], v[208:211], v[94:97]
	v_mfma_f32_16x16x32_bf16 v[86:89], v[138:141], v[208:211], v[86:89]
	v_mfma_f32_16x16x32_bf16 v[78:81], v[130:133], v[216:219], v[78:81]
	v_mfma_f32_16x16x32_bf16 v[70:73], v[138:141], v[216:219], v[70:73]
	v_mfma_f32_16x16x32_bf16 v[126:129], v[134:137], v[196:199], v[126:129]
	v_mfma_f32_16x16x32_bf16 v[118:121], v[142:145], v[196:199], v[118:121]
	v_mfma_f32_16x16x32_bf16 v[110:113], v[134:137], v[204:207], v[110:113]
	v_mfma_f32_16x16x32_bf16 v[102:105], v[142:145], v[204:207], v[102:105]
	v_mfma_f32_16x16x32_bf16 v[94:97], v[134:137], v[212:215], v[94:97]
	v_mfma_f32_16x16x32_bf16 v[86:89], v[142:145], v[212:215], v[86:89]
	v_mfma_f32_16x16x32_bf16 v[78:81], v[134:137], v[220:223], v[78:81]
	v_mfma_f32_16x16x32_bf16 v[70:73], v[142:145], v[220:223], v[70:73]
	s_setprio 0
	s_setprio 1
	v_mfma_f32_16x16x32_bf16 v[122:125], v[146:149], v[174:177], v[122:125]
	v_mfma_f32_16x16x32_bf16 v[114:117], v[154:157], v[174:177], v[114:117]
	v_mfma_f32_16x16x32_bf16 v[106:109], v[146:149], v[200:203], v[106:109]
	v_mfma_f32_16x16x32_bf16 v[98:101], v[154:157], v[200:203], v[98:101]
	v_mfma_f32_16x16x32_bf16 v[90:93], v[146:149], v[208:211], v[90:93]
	v_mfma_f32_16x16x32_bf16 v[82:85], v[154:157], v[208:211], v[82:85]
	v_mfma_f32_16x16x32_bf16 v[74:77], v[146:149], v[216:219], v[74:77]
	v_mfma_f32_16x16x32_bf16 v[66:69], v[154:157], v[216:219], v[66:69]
	v_mfma_f32_16x16x32_bf16 v[122:125], v[150:153], v[196:199], v[122:125]
	v_mfma_f32_16x16x32_bf16 v[114:117], v[158:161], v[196:199], v[114:117]
	v_mfma_f32_16x16x32_bf16 v[106:109], v[150:153], v[204:207], v[106:109]
	v_mfma_f32_16x16x32_bf16 v[98:101], v[158:161], v[204:207], v[98:101]
	s_setprio 2
	s_barrier
	v_mfma_f32_16x16x32_bf16 v[90:93], v[150:153], v[212:215], v[90:93]
	v_mfma_f32_16x16x32_bf16 v[82:85], v[158:161], v[212:215], v[82:85]
	v_mfma_f32_16x16x32_bf16 v[74:77], v[150:153], v[220:223], v[74:77]
	v_mfma_f32_16x16x32_bf16 v[66:69], v[158:161], v[220:223], v[66:69]
	s_setprio 0
	s_add_i32 s71, s71, s7
	s_mov_b32 m0, s71
	ds_read_b128 v[174:177], v194 offset:16384
	ds_read_b128 v[196:199], v194 offset:17408
	ds_read_b128 v[200:203], v194 offset:18432
	ds_read_b128 v[204:207], v194 offset:19456
	ds_read_b128 v[208:211], v194 offset:20480
	ds_read_b128 v[212:215], v194 offset:21504
	ds_read_b128 v[216:219], v194 offset:22528
	ds_read_b128 v[220:223], v194 offset:23552
	global_load_lds_dwordx4 v0, s[42:43]
	s_add_i32 m0, s71, 0x2000
	s_add_u32 s96, s42, 0x40000
	s_addc_u32 s97, s43, 0
	s_add_i32 s3, s3, s7
	global_load_lds_dwordx4 v164, s[42:43]
	s_mov_b32 m0, s3
	s_nop 0
	global_load_lds_dwordx4 v0, s[96:97]
	s_add_i32 m0, s3, 0x2000
	s_nop 0
	global_load_lds_dwordx4 v164, s[96:97]
	s_mov_b32 m0, s9
	s_nop 0
	global_load_lds_dwordx4 v168, s[44:45]
	s_mov_b32 m0, s56
	s_nop 0
	global_load_lds_dwordx4 v166, s[44:45]
	s_waitcnt vmcnt(8)
	s_waitcnt lgkmcnt(0)
	s_setprio 1
	s_barrier
	v_mfma_f32_16x16x32_bf16 v[62:65], v[130:133], v[174:177], v[62:65]
	v_mfma_f32_16x16x32_bf16 v[54:57], v[138:141], v[174:177], v[54:57]
	v_mfma_f32_16x16x32_bf16 v[46:49], v[130:133], v[200:203], v[46:49]
	v_mfma_f32_16x16x32_bf16 v[38:41], v[138:141], v[200:203], v[38:41]
	v_mfma_f32_16x16x32_bf16 v[30:33], v[130:133], v[208:211], v[30:33]
	v_mfma_f32_16x16x32_bf16 v[22:25], v[138:141], v[208:211], v[22:25]
	v_mfma_f32_16x16x32_bf16 v[14:17], v[130:133], v[216:219], v[14:17]
	v_mfma_f32_16x16x32_bf16 v[6:9], v[138:141], v[216:219], v[6:9]
	v_mfma_f32_16x16x32_bf16 v[62:65], v[134:137], v[196:199], v[62:65]
	v_mfma_f32_16x16x32_bf16 v[54:57], v[142:145], v[196:199], v[54:57]
	v_mfma_f32_16x16x32_bf16 v[46:49], v[134:137], v[204:207], v[46:49]
	v_mfma_f32_16x16x32_bf16 v[38:41], v[142:145], v[204:207], v[38:41]
	v_mfma_f32_16x16x32_bf16 v[30:33], v[134:137], v[212:215], v[30:33]
	v_mfma_f32_16x16x32_bf16 v[22:25], v[142:145], v[212:215], v[22:25]
	v_mfma_f32_16x16x32_bf16 v[14:17], v[134:137], v[220:223], v[14:17]
	v_mfma_f32_16x16x32_bf16 v[6:9], v[142:145], v[220:223], v[6:9]
	s_setprio 0
	s_setprio 1
	v_mfma_f32_16x16x32_bf16 v[58:61], v[146:149], v[174:177], v[58:61]
	v_mfma_f32_16x16x32_bf16 v[50:53], v[154:157], v[174:177], v[50:53]
	v_mfma_f32_16x16x32_bf16 v[42:45], v[146:149], v[200:203], v[42:45]
	v_mfma_f32_16x16x32_bf16 v[34:37], v[154:157], v[200:203], v[34:37]
	v_mfma_f32_16x16x32_bf16 v[26:29], v[146:149], v[208:211], v[26:29]
	v_mfma_f32_16x16x32_bf16 v[18:21], v[154:157], v[208:211], v[18:21]
	v_mfma_f32_16x16x32_bf16 v[10:13], v[146:149], v[216:219], v[10:13]
	v_mfma_f32_16x16x32_bf16 v[2:5], v[154:157], v[216:219], v[2:5]
	v_mfma_f32_16x16x32_bf16 v[58:61], v[150:153], v[196:199], v[58:61]
	v_mfma_f32_16x16x32_bf16 v[50:53], v[158:161], v[196:199], v[50:53]
	v_mfma_f32_16x16x32_bf16 v[42:45], v[150:153], v[204:207], v[42:45]
	v_mfma_f32_16x16x32_bf16 v[34:37], v[158:161], v[204:207], v[34:37]
	s_setprio 2
	s_barrier
; #define PG8_STAGE(bufoff, gbase, voff) do { _Pragma("unroll") for (int _i = 0; _i < 2; ++_i) \
;         __builtin_amdgcn_global_load_lds((const unsigned*)((const char*)(gbase) + (voff)[_i]), (LAS unsigned*)(lds + (bufoff) + ldsw + _i * 8192), 16, 0, 0); } while (0)
; #define PG8_LDA(dst, b, h) do { _Pragma("unroll") for (int m = 0; m < 4; ++m) _Pragma("unroll") for (int k = 0; k < 2; ++k) dst[m][k] = *(const LAS bf16x8*)(lds + PG8_SA(b, h) + aoff + m * 2048 + k * 1024); } while (0)
; #define PG8_LDB(dst, b, h) do { _Pragma("unroll") for (int n = 0; n < 2; ++n) _Pragma("unroll") for (int k = 0; k < 2; ++k) dst[n][k] = *(const LAS bf16x8*)(lds + PG8_SB(b, h) + boff + n * 2048 + k * 1024); } while (0)
; #define PG8_MMA(ai, bj, At, Bt) do { __builtin_amdgcn_s_setprio(1); _Pragma("unroll") for (int m = 0; m < 4; ++m) _Pragma("unroll") for (int n = 0; n < 2; ++n) _Pragma("unroll") for (int k = 0; k < 2; ++k) \
;         acc[ai][bj][m][n] = __builtin_amdgcn_mfma_f32_16x16x32_bf16(Bt[n][k], At[m][k], acc[ai][bj][m][n], 0, 0, 0); __builtin_amdgcn_s_setprio(0); } while (0)
; #define PG8_WAIT_V(n) asm volatile("s_waitcnt vmcnt(" #n ")" ::: "memory")
; #define PG8_WAIT_L(n) asm volatile("s_waitcnt lgkmcnt(" #n ")" ::: "memory")
; #define PG8_BAR __builtin_amdgcn_s_barrier()
; #define PG8_SCHED __builtin_amdgcn_sched_barrier(0)
; template <class Epi, class Sched>
; __device__ __forceinline__ void gemm_phase(LAS unsigned char* lds, const Gemm g, Sched S, const Epi& E) {
;     ...
;             PG8_WAIT_V(8); PG8_WAIT_L(0); PG8_BAR; PG8_MMA(1, 0, At, B0); PG8_MMA(1, 1, At, B1); PG8_BAR; PG8_SCHED;
;             PG8_LDB(B0, 1, 0); PG8_LDB(B1, 1, 1); PG8_SCHED; PG8_LDA(At, 1, 0); PG8_STAGE(PG8_SA(0, 1), a2 + hstepA, voffA);
;             PG8_WAIT_V(8); PG8_WAIT_L(0); PG8_BAR; PG8_MMA(0, 0, At, B0); PG8_MMA(0, 1, At, B1); PG8_BAR; PG8_SCHED;
	v_mfma_f32_16x16x32_bf16 v[26:29], v[150:153], v[212:215], v[26:29]
	v_mfma_f32_16x16x32_bf16 v[18:21], v[158:161], v[212:215], v[18:21]
	v_mfma_f32_16x16x32_bf16 v[10:13], v[150:153], v[220:223], v[10:13]
	v_mfma_f32_16x16x32_bf16 v[2:5], v[158:161], v[220:223], v[2:5]
	s_setprio 0
	s_add_i32 s3, 0, 0x18000
	s_add_i32 s71, 0, 0x1c000
	v_add_u32_e32 v142, s3, v183
	v_add_u32_e32 v158, s71, v183
	ds_read_b128 v[130:133], v142
	ds_read_b128 v[134:137], v142 offset:1024
	ds_read_b128 v[138:141], v142 offset:2048
	ds_read_b128 v[142:145], v142 offset:3072
	ds_read_b128 v[146:149], v158
	ds_read_b128 v[150:153], v158 offset:1024
	ds_read_b128 v[154:157], v158 offset:2048
	ds_read_b128 v[158:161], v158 offset:3072
	s_add_u32 s44, s44, 0x40000
	s_addc_u32 s45, s45, 0
	s_mov_b32 m0, s67
	ds_read_b128 v[174:177], v194 offset:32768
	ds_read_b128 v[196:199], v194 offset:33792
	ds_read_b128 v[200:203], v194 offset:34816
	ds_read_b128 v[204:207], v194 offset:35840
	ds_read_b128 v[208:211], v194 offset:36864
	ds_read_b128 v[212:215], v194 offset:37888
	ds_read_b128 v[216:219], v194 offset:38912
	ds_read_b128 v[220:223], v194 offset:39936
	global_load_lds_dwordx4 v168, s[44:45]
	s_mov_b32 m0, s72
	s_nop 0
	global_load_lds_dwordx4 v166, s[44:45]
	s_waitcnt vmcnt(8)
	s_waitcnt lgkmcnt(0)
	s_setprio 1
	s_barrier
	v_mfma_f32_16x16x32_bf16 v[126:129], v[130:133], v[174:177], v[126:129]
	v_mfma_f32_16x16x32_bf16 v[118:121], v[138:141], v[174:177], v[118:121]
	v_mfma_f32_16x16x32_bf16 v[110:113], v[130:133], v[200:203], v[110:113]
	v_mfma_f32_16x16x32_bf16 v[102:105], v[138:141], v[200:203], v[102:105]
	v_mfma_f32_16x16x32_bf16 v[94:97], v[130:133], v[208:211], v[94:97]
	v_mfma_f32_16x16x32_bf16 v[86:89], v[138:141], v[208:211], v[86:89]
	v_mfma_f32_16x16x32_bf16 v[78:81], v[130:133], v[216:219], v[78:81]
	v_mfma_f32_16x16x32_bf16 v[70:73], v[138:141], v[216:219], v[70:73]
	v_mfma_f32_16x16x32_bf16 v[126:129], v[134:137], v[196:199], v[126:129]
	v_mfma_f32_16x16x32_bf16 v[118:121], v[142:145], v[196:199], v[118:121]
	v_mfma_f32_16x16x32_bf16 v[110:113], v[134:137], v[204:207], v[110:113]
	v_mfma_f32_16x16x32_bf16 v[102:105], v[142:145], v[204:207], v[102:105]
	v_mfma_f32_16x16x32_bf16 v[94:97], v[134:137], v[212:215], v[94:97]
	v_mfma_f32_16x16x32_bf16 v[86:89], v[142:145], v[212:215], v[86:89]
	v_mfma_f32_16x16x32_bf16 v[78:81], v[134:137], v[220:223], v[78:81]
	v_mfma_f32_16x16x32_bf16 v[70:73], v[142:145], v[220:223], v[70:73]
	s_setprio 0
	s_setprio 1
	v_mfma_f32_16x16x32_bf16 v[122:125], v[146:149], v[174:177], v[122:125]
	v_mfma_f32_16x16x32_bf16 v[114:117], v[154:157], v[174:177], v[114:117]
	v_mfma_f32_16x16x32_bf16 v[106:109], v[146:149], v[200:203], v[106:109]
	v_mfma_f32_16x16x32_bf16 v[98:101], v[154:157], v[200:203], v[98:101]
	v_mfma_f32_16x16x32_bf16 v[90:93], v[146:149], v[208:211], v[90:93]
	v_mfma_f32_16x16x32_bf16 v[82:85], v[154:157], v[208:211], v[82:85]
	v_mfma_f32_16x16x32_bf16 v[74:77], v[146:149], v[216:219], v[74:77]
	v_mfma_f32_16x16x32_bf16 v[66:69], v[154:157], v[216:219], v[66:69]
	v_mfma_f32_16x16x32_bf16 v[122:125], v[150:153], v[196:199], v[122:125]
	v_mfma_f32_16x16x32_bf16 v[114:117], v[158:161], v[196:199], v[114:117]
	v_mfma_f32_16x16x32_bf16 v[106:109], v[150:153], v[204:207], v[106:109]
	v_mfma_f32_16x16x32_bf16 v[98:101], v[158:161], v[204:207], v[98:101]
	s_setprio 2
	s_barrier
; #define PG8_STAGE(bufoff, gbase, voff) do { _Pragma("unroll") for (int _i = 0; _i < 2; ++_i) \
;         __builtin_amdgcn_global_load_lds((const unsigned*)((const char*)(gbase) + (voff)[_i]), (LAS unsigned*)(lds + (bufoff) + ldsw + _i * 8192), 16, 0, 0); } while (0)
; #define PG8_LDA(dst, b, h) do { _Pragma("unroll") for (int m = 0; m < 4; ++m) _Pragma("unroll") for (int k = 0; k < 2; ++k) dst[m][k] = *(const LAS bf16x8*)(lds + PG8_SA(b, h) + aoff + m * 2048 + k * 1024); } while (0)
; #define PG8_MMA(ai, bj, At, Bt) do { __builtin_amdgcn_s_setprio(1); _Pragma("unroll") for (int m = 0; m < 4; ++m) _Pragma("unroll") for (int n = 0; n < 2; ++n) _Pragma("unroll") for (int k = 0; k < 2; ++k) \
;         acc[ai][bj][m][n] = __builtin_amdgcn_mfma_f32_16x16x32_bf16(Bt[n][k], At[m][k], acc[ai][bj][m][n], 0, 0, 0); __builtin_amdgcn_s_setprio(0); } while (0)
; #define PG8_WAIT_V(n) asm volatile("s_waitcnt vmcnt(" #n ")" ::: "memory")
; #define PG8_WAIT_L(n) asm volatile("s_waitcnt lgkmcnt(" #n ")" ::: "memory")
; #define PG8_BAR __builtin_amdgcn_s_barrier()
; #define PG8_SCHED __builtin_amdgcn_sched_barrier(0)
; template <class Epi, class Sched>
; __device__ __forceinline__ void gemm_phase(LAS unsigned char* lds, const Gemm g, Sched S, const Epi& E) {
;     ...
;             PG8_WAIT_V(8); PG8_WAIT_L(0); PG8_BAR; PG8_MMA(0, 0, At, B0); PG8_MMA(0, 1, At, B1); PG8_BAR; PG8_SCHED;
;             PG8_LDA(At, 1, 1); PG8_STAGE(PG8_SB(1, 0), b3, voffB); PG8_STAGE(PG8_SB(1, 1), b3 + hstepB, voffB); PG8_STAGE(PG8_SA(1, 0), a3, voffA);
;             PG8_WAIT_V(8); PG8_WAIT_L(0); PG8_BAR; PG8_MMA(1, 0, At, B0); PG8_MMA(1, 1, At, B1); PG8_BAR; PG8_SCHED;
;         }
	v_mfma_f32_16x16x32_bf16 v[90:93], v[150:153], v[212:215], v[90:93]
	v_mfma_f32_16x16x32_bf16 v[82:85], v[158:161], v[212:215], v[82:85]
	v_mfma_f32_16x16x32_bf16 v[74:77], v[150:153], v[220:223], v[74:77]
	v_mfma_f32_16x16x32_bf16 v[66:69], v[158:161], v[220:223], v[66:69]
	s_setprio 0
	s_add_i32 s3, s3, s7
	s_add_u32 s100, s42, 0x80
	s_addc_u32 s101, s43, 0
	s_mov_b32 m0, s3
	ds_read_b128 v[174:177], v194 offset:49152
	ds_read_b128 v[196:199], v194 offset:50176
	ds_read_b128 v[200:203], v194 offset:51200
	ds_read_b128 v[204:207], v194 offset:52224
	ds_read_b128 v[208:211], v194 offset:53248
	ds_read_b128 v[212:215], v194 offset:54272
	ds_read_b128 v[216:219], v194 offset:55296
	ds_read_b128 v[220:223], v194 offset:56320
	global_load_lds_dwordx4 v0, s[100:101]
	s_add_i32 m0, s3, 0x2000
	s_add_u32 s42, s42, 0x40080
	s_addc_u32 s43, s43, 0
	s_add_u32 s96, s44, 0xfffc0080
	s_addc_u32 s97, s45, -1
	s_add_i32 s3, s71, s7
	global_load_lds_dwordx4 v164, s[100:101]
	s_mov_b32 m0, s3
	s_nop 0
	global_load_lds_dwordx4 v0, s[42:43]
	s_add_i32 m0, s3, 0x2000
	s_nop 0
	global_load_lds_dwordx4 v164, s[42:43]
	s_mov_b32 m0, s73
	s_nop 0
	global_load_lds_dwordx4 v168, s[96:97]
	s_mov_b32 m0, s76
	s_nop 0
	global_load_lds_dwordx4 v166, s[96:97]
	s_waitcnt vmcnt(8)
	s_waitcnt lgkmcnt(0)
	s_setprio 1
	s_barrier
	v_mfma_f32_16x16x32_bf16 v[62:65], v[130:133], v[174:177], v[62:65]
	v_mfma_f32_16x16x32_bf16 v[54:57], v[138:141], v[174:177], v[54:57]
	v_mfma_f32_16x16x32_bf16 v[46:49], v[130:133], v[200:203], v[46:49]
	v_mfma_f32_16x16x32_bf16 v[38:41], v[138:141], v[200:203], v[38:41]
	v_mfma_f32_16x16x32_bf16 v[30:33], v[130:133], v[208:211], v[30:33]
	v_mfma_f32_16x16x32_bf16 v[22:25], v[138:141], v[208:211], v[22:25]
	v_mfma_f32_16x16x32_bf16 v[14:17], v[130:133], v[216:219], v[14:17]
	v_mfma_f32_16x16x32_bf16 v[6:9], v[138:141], v[216:219], v[6:9]
	v_mfma_f32_16x16x32_bf16 v[62:65], v[134:137], v[196:199], v[62:65]
	v_mfma_f32_16x16x32_bf16 v[54:57], v[142:145], v[196:199], v[54:57]
	v_mfma_f32_16x16x32_bf16 v[46:49], v[134:137], v[204:207], v[46:49]
	v_mfma_f32_16x16x32_bf16 v[38:41], v[142:145], v[204:207], v[38:41]
	v_mfma_f32_16x16x32_bf16 v[30:33], v[134:137], v[212:215], v[30:33]
	v_mfma_f32_16x16x32_bf16 v[22:25], v[142:145], v[212:215], v[22:25]
	v_mfma_f32_16x16x32_bf16 v[14:17], v[134:137], v[220:223], v[14:17]
	v_mfma_f32_16x16x32_bf16 v[6:9], v[142:145], v[220:223], v[6:9]
	s_setprio 0
	s_setprio 1
	v_mfma_f32_16x16x32_bf16 v[58:61], v[146:149], v[174:177], v[58:61]
	v_mfma_f32_16x16x32_bf16 v[50:53], v[154:157], v[174:177], v[50:53]
	v_mfma_f32_16x16x32_bf16 v[42:45], v[146:149], v[200:203], v[42:45]
	v_mfma_f32_16x16x32_bf16 v[34:37], v[154:157], v[200:203], v[34:37]
	v_mfma_f32_16x16x32_bf16 v[26:29], v[146:149], v[208:211], v[26:29]
	v_mfma_f32_16x16x32_bf16 v[18:21], v[154:157], v[208:211], v[18:21]
	v_mfma_f32_16x16x32_bf16 v[10:13], v[146:149], v[216:219], v[10:13]
	v_mfma_f32_16x16x32_bf16 v[2:5], v[154:157], v[216:219], v[2:5]
	v_mfma_f32_16x16x32_bf16 v[58:61], v[150:153], v[196:199], v[58:61]
	v_mfma_f32_16x16x32_bf16 v[50:53], v[158:161], v[196:199], v[50:53]
	v_mfma_f32_16x16x32_bf16 v[42:45], v[150:153], v[204:207], v[42:45]
	v_mfma_f32_16x16x32_bf16 v[34:37], v[158:161], v[204:207], v[34:37]
	s_setprio 2
	s_barrier
	v_mfma_f32_16x16x32_bf16 v[26:29], v[150:153], v[212:215], v[26:29]
	v_mfma_f32_16x16x32_bf16 v[18:21], v[158:161], v[212:215], v[18:21]
	v_mfma_f32_16x16x32_bf16 v[10:13], v[150:153], v[220:223], v[10:13]
	v_mfma_f32_16x16x32_bf16 v[2:5], v[158:161], v[220:223], v[2:5]
	s_setprio 0
	s_add_i32 s70, s70, 2
	s_add_u32 s64, s64, 0x100
	s_addc_u32 s65, s65, 0
	s_add_u32 s10, s10, 0x100
	s_addc_u32 s11, s11, 0
	s_cmp_gt_u32 s70, 13
	s_cbranch_scc0 .LBB0_770
	s_and_b64 vcc, exec, s[30:31]
	s_cbranch_vccz .LBB0_773
	s_barrier
